# grid barrier: non-leader workgroups poll the cross-XCD release generation directly (one relay hop less per barrier)
# speedup vs baseline: 1.0008x; 1.0008x over previous
.LBB0_783:
	s_or_b64 exec, exec, s[4:5]
	v_cvt_f32_u32_e32 v6, v3
	s_waitcnt vmcnt(0)
	v_readfirstlane_b32 s4, v5
	v_sub_u32_e32 v5, 0, v3
	v_rcp_iflag_f32_e32 v6, v6
	v_add_u32_e32 v7, s4, v0
	v_mul_f32_e32 v6, 0x4f7ffffe, v6
	v_cvt_u32_f32_e32 v6, v6
	v_mul_lo_u32 v0, v5, v6
	v_mul_hi_u32 v0, v6, v0
	v_add_u32_e32 v0, v6, v0
	v_mul_hi_u32 v0, v7, v0
	v_mul_lo_u32 v5, v0, v3
	v_sub_u32_e32 v5, v7, v5
	v_add_u32_e32 v6, 1, v0
	v_cmp_ge_u32_e32 vcc, v5, v3
	s_nop 1
	v_cndmask_b32_e32 v0, v0, v6, vcc
	v_sub_u32_e32 v6, v5, v3
	v_cndmask_b32_e32 v5, v5, v6, vcc
	v_add_u32_e32 v6, 1, v0
	v_cmp_ge_u32_e32 vcc, v5, v3
	v_add_u32_e32 v5, 1, v7
	s_nop 0
	v_cndmask_b32_e32 v0, v0, v6, vcc
	v_mul_lo_u32 v6, v3, v0
	v_add_u32_e32 v3, v6, v3
	v_cmp_ne_u32_e32 vcc, v5, v3
	s_and_saveexec_b64 s[4:5], vcc
	s_xor_b64 s[4:5], exec, s[4:5]
	s_cbranch_execz .LBB0_797
	v_readlane_b32 s6, v253, 17
	v_readlane_b32 s7, v253, 18
	s_waitcnt lgkmcnt(0)
	s_nop 3
	global_load_dword v2, v1, s[6:7] sc1
	s_waitcnt vmcnt(0)
	v_cmp_eq_u32_e32 vcc, v2, v0
	s_and_saveexec_b64 s[6:7], vcc
	s_cbranch_execz .LBB0_796
	s_mov_b32 s18, 1
	s_mov_b64 s[8:9], 0
	s_branch .LBB0_787
